# row sum-of-squares cross-lane reduction in residual epilogues by lane swaps instead of LDS bpermute
# speedup vs baseline: 1.0001x; 1.0001x over previous
.LBB0_378:
	v_pk_mul_f32 v[154:155], v[190:191], v[190:191]
	v_pk_mul_f32 v[156:157], v[192:193], v[192:193]
	v_pk_mul_f32 v[160:161], v[202:203], v[202:203]
	v_pk_mul_f32 v[192:193], v[206:207], v[206:207]
	v_pk_mul_f32 v[202:203], v[208:209], v[208:209]
	v_add_f32_e32 v156, v156, v157
	v_add_f32_e32 v154, v154, v155
	v_pk_mul_f32 v[190:191], v[204:205], v[204:205]
	v_pk_mul_f32 v[158:159], v[158:159], v[158:159]
	v_pk_mul_f32 v[188:189], v[188:189], v[188:189]
	v_add_f32_e32 v165, v202, v203
	v_add_f32_e32 v171, v192, v193
	v_add_f32_e32 v154, v154, v156
	v_and_b32_e32 v156, 64, v217
	v_add_f32_e32 v165, v171, v165
	v_add_f32_e32 v171, v188, v189
	v_add_f32_e32 v158, v158, v159
	v_add_f32_e32 v159, v190, v191
	v_add_f32_e32 v160, v160, v161
	v_xor_b32_e32 v155, 16, v217
	v_add_u32_e32 v156, 64, v156
	v_add_f32_e32 v158, v158, v171
	v_add_f32_e32 v159, v160, v159
	v_cmp_lt_i32_e32 vcc, v155, v156
	v_add_f32_e32 v158, v158, v165
	v_add_f32_e32 v154, v154, v159
	v_cndmask_b32_e32 v155, v217, v155, vcc
	v_add_f32_e32 v154, v154, v158
	v_lshlrev_b32_e32 v220, 2, v155
	v_mov_b32_e32 v155, v154
	s_nop 1
	v_permlane16_swap_b32_e32 v154, v155
	s_lshl_b32 s52, s68, 2
	v_cmp_eq_u32_e64 s[14:15], 0, v163
	s_ashr_i32 s53, s52, 31
	s_mov_b64 s[64:65], s[36:37]
	s_waitcnt lgkmcnt(0)
	v_add_f32_e32 v154, v154, v155
	v_xor_b32_e32 v155, 32, v217
	v_cmp_lt_i32_e32 vcc, v155, v156
	s_nop 1
	v_cndmask_b32_e32 v155, v217, v155, vcc
	v_lshlrev_b32_e32 v221, 2, v155
	v_mov_b32_e32 v155, v154
	s_nop 1
	v_permlane32_swap_b32_e32 v154, v155
	s_and_saveexec_b64 s[62:63], s[14:15]
	s_cbranch_execz .LBB0_384
	v_ashrrev_i32_e32 v163, 31, v162
	s_waitcnt lgkmcnt(0)
	v_add_f32_e32 v156, v154, v155
	v_lshlrev_b64 v[154:155], 6, v[162:163]
	v_lshl_add_u64 v[154:155], s[46:47], 0, v[154:155]
	v_lshl_add_u64 v[154:155], s[52:53], 2, v[154:155]
	s_lshl_b32 s26, s77, 2
	v_lshl_add_u64 v[154:155], v[154:155], 0, s[26:27]
	s_mov_b64 s[64:65], -1
	s_and_b64 vcc, exec, s[54:55]
	s_cbranch_vccz .LBB0_381
	global_store_dword v[154:155], v156, off
	s_mov_b64 s[64:65], 0

.LBB0_392:
	v_pk_mul_f32 v[146:147], v[154:155], v[154:155]
	v_pk_mul_f32 v[148:149], v[156:157], v[156:157]
	v_pk_mul_f32 v[150:151], v[158:159], v[158:159]
	v_pk_mul_f32 v[154:155], v[160:161], v[160:161]
	v_pk_mul_f32 v[152:153], v[152:153], v[152:153]
	v_pk_mul_f32 v[156:157], v[182:183], v[182:183]
	v_pk_mul_f32 v[158:159], v[184:185], v[184:185]
	v_pk_mul_f32 v[160:161], v[186:187], v[186:187]
	v_add_f32_e32 v158, v158, v159
	v_add_f32_e32 v160, v160, v161
	v_add_f32_e32 v156, v156, v157
	v_add_f32_e32 v152, v152, v153
	v_add_f32_e32 v153, v154, v155
	v_add_f32_e32 v150, v150, v151
	v_add_f32_e32 v148, v148, v149
	v_add_f32_e32 v146, v146, v147
	v_add_f32_e32 v158, v158, v160
	v_add_f32_e32 v152, v152, v156
	v_add_f32_e32 v150, v150, v153
	v_add_f32_e32 v146, v146, v148
	v_add_f32_e32 v152, v152, v158
	v_add_f32_e32 v146, v146, v150
	v_add_f32_e32 v146, v146, v152
	v_mov_b32_e32 v147, v146
	s_nop 1
	v_permlane16_swap_b32_e32 v146, v147
	s_mov_b64 s[62:63], s[36:37]
	s_waitcnt lgkmcnt(0)
	v_add_f32_e32 v146, v146, v147
	v_mov_b32_e32 v147, v146
	s_nop 1
	v_permlane32_swap_b32_e32 v146, v147
	s_and_saveexec_b64 s[54:55], s[14:15]
	s_cbranch_execz .LBB0_398
	v_ashrrev_i32_e32 v179, 31, v178
	s_waitcnt lgkmcnt(0)
	v_add_f32_e32 v148, v146, v147
	v_lshlrev_b64 v[146:147], 6, v[178:179]
	v_lshl_add_u64 v[146:147], s[46:47], 0, v[146:147]
	v_lshl_add_u64 v[146:147], s[52:53], 2, v[146:147]
	s_lshl_b32 s26, s77, 2
	v_lshl_add_u64 v[146:147], v[146:147], 0, s[26:27]
	s_and_b64 vcc, exec, s[12:13]
	s_mov_b64 s[62:63], -1
	s_cbranch_vccnz .LBB0_395
	s_mov_b64 s[62:63], 0
	global_store_dword v[146:147], v148, off

.LBB0_406:
	v_pk_mul_f32 v[138:139], v[146:147], v[146:147]
	v_pk_mul_f32 v[140:141], v[148:149], v[148:149]
	v_pk_mul_f32 v[142:143], v[150:151], v[150:151]
	v_pk_mul_f32 v[146:147], v[152:153], v[152:153]
	v_pk_mul_f32 v[144:145], v[144:145], v[144:145]
	v_pk_mul_f32 v[148:149], v[154:155], v[154:155]
	v_pk_mul_f32 v[150:151], v[156:157], v[156:157]
	v_pk_mul_f32 v[152:153], v[158:159], v[158:159]
	v_add_f32_e32 v150, v150, v151
	v_add_f32_e32 v152, v152, v153
	v_add_f32_e32 v148, v148, v149
	v_add_f32_e32 v144, v144, v145
	v_add_f32_e32 v145, v146, v147
	v_add_f32_e32 v142, v142, v143
	v_add_f32_e32 v140, v140, v141
	v_add_f32_e32 v138, v138, v139
	v_add_f32_e32 v150, v150, v152
	v_add_f32_e32 v144, v144, v148
	v_add_f32_e32 v142, v142, v145
	v_add_f32_e32 v138, v138, v140
	v_add_f32_e32 v144, v144, v150
	v_add_f32_e32 v138, v138, v142
	v_add_f32_e32 v138, v138, v144
	v_mov_b32_e32 v139, v138
	s_nop 1
	v_permlane16_swap_b32_e32 v138, v139
	s_mov_b64 s[62:63], s[36:37]
	s_waitcnt lgkmcnt(0)
	v_add_f32_e32 v138, v138, v139
	v_mov_b32_e32 v139, v138
	s_nop 1
	v_permlane32_swap_b32_e32 v138, v139
	s_and_saveexec_b64 s[54:55], s[14:15]
	s_cbranch_execz .LBB0_412
	v_ashrrev_i32_e32 v171, 31, v170
	s_waitcnt lgkmcnt(0)
	v_add_f32_e32 v140, v138, v139
	v_lshlrev_b64 v[138:139], 6, v[170:171]
	v_lshl_add_u64 v[138:139], s[46:47], 0, v[138:139]
	v_lshl_add_u64 v[138:139], s[52:53], 2, v[138:139]
	s_lshl_b32 s26, s77, 2
	v_lshl_add_u64 v[138:139], v[138:139], 0, s[26:27]
	s_and_b64 vcc, exec, s[12:13]
	s_mov_b64 s[62:63], -1
	s_cbranch_vccnz .LBB0_409
	s_mov_b64 s[62:63], 0
	global_store_dword v[138:139], v140, off

.LBB0_420:
	v_pk_mul_f32 v[130:131], v[138:139], v[138:139]
	v_pk_mul_f32 v[132:133], v[140:141], v[140:141]
	v_pk_mul_f32 v[134:135], v[142:143], v[142:143]
	v_pk_mul_f32 v[138:139], v[144:145], v[144:145]
	v_pk_mul_f32 v[136:137], v[136:137], v[136:137]
	v_pk_mul_f32 v[140:141], v[146:147], v[146:147]
	v_pk_mul_f32 v[142:143], v[148:149], v[148:149]
	v_pk_mul_f32 v[144:145], v[150:151], v[150:151]
	v_add_f32_e32 v142, v142, v143
	v_add_f32_e32 v144, v144, v145
	v_add_f32_e32 v140, v140, v141
	v_add_f32_e32 v136, v136, v137
	v_add_f32_e32 v137, v138, v139
	v_add_f32_e32 v134, v134, v135
	v_add_f32_e32 v132, v132, v133
	v_add_f32_e32 v130, v130, v131
	v_add_f32_e32 v142, v142, v144
	v_add_f32_e32 v136, v136, v140
	v_add_f32_e32 v134, v134, v137
	v_add_f32_e32 v130, v130, v132
	v_add_f32_e32 v136, v136, v142
	v_add_f32_e32 v130, v130, v134
	v_add_f32_e32 v130, v130, v136
	v_mov_b32_e32 v131, v130
	s_nop 1
	v_permlane16_swap_b32_e32 v130, v131
	s_waitcnt lgkmcnt(0)
	v_add_f32_e32 v130, v130, v131
	v_mov_b32_e32 v131, v130
	s_nop 1
	v_permlane32_swap_b32_e32 v130, v131
	s_and_saveexec_b64 s[54:55], s[14:15]
	s_cbranch_execz .LBB0_425
	v_ashrrev_i32_e32 v165, 31, v164
	s_waitcnt lgkmcnt(0)
	v_add_f32_e32 v132, v130, v131
	v_lshlrev_b64 v[130:131], 6, v[164:165]
	v_lshl_add_u64 v[130:131], s[46:47], 0, v[130:131]
	v_lshl_add_u64 v[130:131], s[52:53], 2, v[130:131]
	s_lshl_b32 s26, s77, 2
	v_lshl_add_u64 v[130:131], v[130:131], 0, s[26:27]
	s_and_b64 vcc, exec, s[12:13]
	s_mov_b64 s[62:63], -1
	s_cbranch_vccnz .LBB0_423
	s_mov_b64 s[62:63], 0
	global_store_dword v[130:131], v132, off

.LBB0_433:
	v_pk_mul_f32 v[156:157], v[192:193], v[192:193]
	v_pk_mul_f32 v[158:159], v[202:203], v[202:203]
	v_pk_mul_f32 v[192:193], v[206:207], v[206:207]
	v_pk_mul_f32 v[202:203], v[208:209], v[208:209]
	v_pk_mul_f32 v[154:155], v[190:191], v[190:191]
	v_pk_mul_f32 v[190:191], v[204:205], v[204:205]
	v_pk_mul_f32 v[160:161], v[160:161], v[160:161]
	v_pk_mul_f32 v[188:189], v[188:189], v[188:189]
	v_add_f32_e32 v163, v202, v203
	v_add_f32_e32 v169, v192, v193
	v_add_f32_e32 v163, v169, v163
	v_add_f32_e32 v169, v188, v189
	v_add_f32_e32 v160, v160, v161
	v_add_f32_e32 v161, v190, v191
	v_add_f32_e32 v158, v158, v159
	v_add_f32_e32 v156, v156, v157
	v_add_f32_e32 v154, v154, v155
	v_add_f32_e32 v160, v160, v169
	v_add_f32_e32 v158, v158, v161
	v_add_f32_e32 v154, v154, v156
	v_add_f32_e32 v160, v160, v163
	v_add_f32_e32 v154, v154, v158
	v_add_f32_e32 v154, v154, v160
	v_mov_b32_e32 v155, v154
	s_nop 1
	v_permlane16_swap_b32_e32 v154, v155
	s_mov_b64 s[62:63], s[36:37]
	s_waitcnt lgkmcnt(0)
	v_add_f32_e32 v154, v154, v155
	v_mov_b32_e32 v155, v154
	s_nop 1
	v_permlane32_swap_b32_e32 v154, v155
	s_and_saveexec_b64 s[54:55], s[14:15]
	s_cbranch_execz .LBB0_439
	v_ashrrev_i32_e32 v185, 31, v184
	s_waitcnt lgkmcnt(0)
	v_add_f32_e32 v156, v154, v155
	v_lshlrev_b64 v[154:155], 6, v[184:185]
	v_lshl_add_u64 v[154:155], s[46:47], 0, v[154:155]
	v_lshl_add_u64 v[154:155], s[52:53], 2, v[154:155]
	s_lshl_b32 s26, s77, 2
	v_lshl_add_u64 v[154:155], v[154:155], 0, s[26:27]
	s_and_b64 vcc, exec, s[12:13]
	s_mov_b64 s[62:63], -1
	s_cbranch_vccnz .LBB0_436
	s_mov_b64 s[62:63], 0
	global_store_dword v[154:155], v156, off

.LBB0_447:
	v_pk_mul_f32 v[146:147], v[154:155], v[154:155]
	v_pk_mul_f32 v[148:149], v[156:157], v[156:157]
	v_pk_mul_f32 v[150:151], v[158:159], v[158:159]
	v_pk_mul_f32 v[154:155], v[160:161], v[160:161]
	v_pk_mul_f32 v[152:153], v[152:153], v[152:153]
	v_pk_mul_f32 v[156:157], v[180:181], v[180:181]
	v_pk_mul_f32 v[158:159], v[182:183], v[182:183]
	v_pk_mul_f32 v[160:161], v[184:185], v[184:185]
	v_add_f32_e32 v158, v158, v159
	v_add_f32_e32 v160, v160, v161
	v_add_f32_e32 v156, v156, v157
	v_add_f32_e32 v152, v152, v153
	v_add_f32_e32 v153, v154, v155
	v_add_f32_e32 v150, v150, v151
	v_add_f32_e32 v148, v148, v149
	v_add_f32_e32 v146, v146, v147
	v_add_f32_e32 v158, v158, v160
	v_add_f32_e32 v152, v152, v156
	v_add_f32_e32 v150, v150, v153
	v_add_f32_e32 v146, v146, v148
	v_add_f32_e32 v152, v152, v158
	v_add_f32_e32 v146, v146, v150
	v_add_f32_e32 v146, v146, v152
	v_mov_b32_e32 v147, v146
	s_nop 1
	v_permlane16_swap_b32_e32 v146, v147
	s_mov_b64 s[62:63], s[36:37]
	s_waitcnt lgkmcnt(0)
	v_add_f32_e32 v146, v146, v147
	v_mov_b32_e32 v147, v146
	s_nop 1
	v_permlane32_swap_b32_e32 v146, v147
	s_and_saveexec_b64 s[54:55], s[14:15]
	s_cbranch_execz .LBB0_453
	v_ashrrev_i32_e32 v177, 31, v176
	s_waitcnt lgkmcnt(0)
	v_add_f32_e32 v148, v146, v147
	v_lshlrev_b64 v[146:147], 6, v[176:177]
	v_lshl_add_u64 v[146:147], s[46:47], 0, v[146:147]
	v_lshl_add_u64 v[146:147], s[52:53], 2, v[146:147]
	s_lshl_b32 s26, s77, 2
	v_lshl_add_u64 v[146:147], v[146:147], 0, s[26:27]
	s_and_b64 vcc, exec, s[12:13]
	s_mov_b64 s[62:63], -1
	s_cbranch_vccnz .LBB0_450
	s_mov_b64 s[62:63], 0
	global_store_dword v[146:147], v148, off

.LBB0_461:
	v_pk_mul_f32 v[138:139], v[146:147], v[146:147]
	v_pk_mul_f32 v[140:141], v[148:149], v[148:149]
	v_pk_mul_f32 v[142:143], v[150:151], v[150:151]
	v_pk_mul_f32 v[146:147], v[152:153], v[152:153]
	v_pk_mul_f32 v[144:145], v[144:145], v[144:145]
	v_pk_mul_f32 v[148:149], v[154:155], v[154:155]
	v_pk_mul_f32 v[150:151], v[156:157], v[156:157]
	v_pk_mul_f32 v[152:153], v[158:159], v[158:159]
	v_add_f32_e32 v150, v150, v151
	v_add_f32_e32 v152, v152, v153
	v_add_f32_e32 v148, v148, v149
	v_add_f32_e32 v144, v144, v145
	v_add_f32_e32 v145, v146, v147
	v_add_f32_e32 v142, v142, v143
	v_add_f32_e32 v140, v140, v141
	v_add_f32_e32 v138, v138, v139
	v_add_f32_e32 v150, v150, v152
	v_add_f32_e32 v144, v144, v148
	v_add_f32_e32 v142, v142, v145
	v_add_f32_e32 v138, v138, v140
	v_add_f32_e32 v144, v144, v150
	v_add_f32_e32 v138, v138, v142
	v_add_f32_e32 v138, v138, v144
	v_mov_b32_e32 v139, v138
	s_nop 1
	v_permlane16_swap_b32_e32 v138, v139
	s_mov_b64 s[62:63], s[36:37]
	s_waitcnt lgkmcnt(0)
	v_add_f32_e32 v138, v138, v139
	v_mov_b32_e32 v139, v138
	s_nop 1
	v_permlane32_swap_b32_e32 v138, v139
	s_and_saveexec_b64 s[54:55], s[14:15]
	s_cbranch_execz .LBB0_467
	v_ashrrev_i32_e32 v169, 31, v168
	s_waitcnt lgkmcnt(0)
	v_add_f32_e32 v140, v138, v139
	v_lshlrev_b64 v[138:139], 6, v[168:169]
	v_lshl_add_u64 v[138:139], s[46:47], 0, v[138:139]
	v_lshl_add_u64 v[138:139], s[52:53], 2, v[138:139]
	s_lshl_b32 s26, s77, 2
	v_lshl_add_u64 v[138:139], v[138:139], 0, s[26:27]
	s_and_b64 vcc, exec, s[12:13]
	s_mov_b64 s[62:63], -1
	s_cbranch_vccnz .LBB0_464
	s_mov_b64 s[62:63], 0
	global_store_dword v[138:139], v140, off

.LBB0_475:
	v_pk_mul_f32 v[130:131], v[138:139], v[138:139]
	v_pk_mul_f32 v[132:133], v[140:141], v[140:141]
	v_pk_mul_f32 v[134:135], v[142:143], v[142:143]
	v_pk_mul_f32 v[138:139], v[144:145], v[144:145]
	v_pk_mul_f32 v[136:137], v[136:137], v[136:137]
	v_pk_mul_f32 v[140:141], v[146:147], v[146:147]
	v_pk_mul_f32 v[142:143], v[148:149], v[148:149]
	v_pk_mul_f32 v[144:145], v[150:151], v[150:151]
	v_add_f32_e32 v142, v142, v143
	v_add_f32_e32 v144, v144, v145
	v_add_f32_e32 v140, v140, v141
	v_add_f32_e32 v136, v136, v137
	v_add_f32_e32 v137, v138, v139
	v_add_f32_e32 v134, v134, v135
	v_add_f32_e32 v132, v132, v133
	v_add_f32_e32 v130, v130, v131
	v_add_f32_e32 v142, v142, v144
	v_add_f32_e32 v136, v136, v140
	v_add_f32_e32 v134, v134, v137
	v_add_f32_e32 v130, v130, v132
	v_add_f32_e32 v136, v136, v142
	v_add_f32_e32 v130, v130, v134
	v_add_f32_e32 v130, v130, v136
	v_mov_b32_e32 v131, v130
	s_nop 1
	v_permlane16_swap_b32_e32 v130, v131
	s_waitcnt lgkmcnt(0)
	v_add_f32_e32 v130, v130, v131
	v_mov_b32_e32 v131, v130
	s_nop 1
	v_permlane32_swap_b32_e32 v130, v131
	s_and_saveexec_b64 s[50:51], s[14:15]
	s_cbranch_execz .LBB0_480
	v_ashrrev_i32_e32 v163, 31, v162
	s_waitcnt lgkmcnt(0)
	v_add_f32_e32 v132, v130, v131
	v_lshlrev_b64 v[130:131], 6, v[162:163]
	v_lshl_add_u64 v[130:131], s[46:47], 0, v[130:131]
	v_lshl_add_u64 v[130:131], s[52:53], 2, v[130:131]
	s_lshl_b32 s26, s77, 2
	v_lshl_add_u64 v[130:131], v[130:131], 0, s[26:27]
	s_and_b64 vcc, exec, s[12:13]
	s_mov_b64 s[12:13], -1
	s_cbranch_vccnz .LBB0_478
	s_mov_b64 s[12:13], 0
	global_store_dword v[130:131], v132, off

.LBB0_1533:
	v_pk_mul_f32 v[154:155], v[190:191], v[190:191]
	v_pk_mul_f32 v[156:157], v[192:193], v[192:193]
	v_pk_mul_f32 v[158:159], v[158:159], v[158:159]
	v_pk_mul_f32 v[160:161], v[160:161], v[160:161]
	v_add_f32_e32 v156, v156, v157
	v_add_f32_e32 v154, v154, v155
	v_pk_mul_f32 v[188:189], v[202:203], v[202:203]
	v_pk_mul_f32 v[190:191], v[204:205], v[204:205]
	v_pk_mul_f32 v[192:193], v[206:207], v[206:207]
	v_pk_mul_f32 v[202:203], v[208:209], v[208:209]
	v_add_f32_e32 v160, v160, v161
	v_add_f32_e32 v158, v158, v159
	v_add_f32_e32 v154, v154, v156
	v_and_b32_e32 v156, 64, v215
	v_add_f32_e32 v165, v202, v203
	v_add_f32_e32 v171, v192, v193
	v_add_f32_e32 v158, v158, v160
	v_add_f32_e32 v159, v190, v191
	v_add_f32_e32 v160, v188, v189
	v_xor_b32_e32 v155, 16, v215
	v_add_u32_e32 v156, 64, v156
	v_add_f32_e32 v165, v171, v165
	v_add_f32_e32 v159, v160, v159
	v_cmp_lt_i32_e32 vcc, v155, v156
	v_add_f32_e32 v158, v158, v165
	v_add_f32_e32 v154, v154, v159
	v_cndmask_b32_e32 v155, v215, v155, vcc
	v_add_f32_e32 v154, v154, v158
	v_lshlrev_b32_e32 v218, 2, v155
	v_mov_b32_e32 v155, v154
	s_nop 1
	v_permlane16_swap_b32_e32 v154, v155
	s_lshl_b32 s52, s14, 2
	v_cmp_eq_u32_e64 s[12:13], 0, v163
	s_ashr_i32 s53, s52, 31
	s_mov_b64 s[58:59], s[36:37]
	s_waitcnt lgkmcnt(0)
	v_add_f32_e32 v154, v154, v155
	v_xor_b32_e32 v155, 32, v215
	v_cmp_lt_i32_e32 vcc, v155, v156
	s_nop 1
	v_cndmask_b32_e32 v155, v215, v155, vcc
	v_lshlrev_b32_e32 v219, 2, v155
	v_mov_b32_e32 v155, v154
	s_nop 1
	v_permlane32_swap_b32_e32 v154, v155
	s_and_saveexec_b64 s[56:57], s[12:13]
	s_cbranch_execz .LBB0_1539
	v_ashrrev_i32_e32 v163, 31, v162
	s_waitcnt lgkmcnt(0)
	v_add_f32_e32 v156, v154, v155
	v_lshlrev_b64 v[154:155], 6, v[162:163]
	v_lshl_add_u64 v[154:155], s[2:3], 0, v[154:155]
	v_lshl_add_u64 v[154:155], s[52:53], 2, v[154:155]
	s_lshl_b32 s26, s69, 2
	v_lshl_add_u64 v[154:155], v[154:155], 0, s[26:27]
	s_mov_b64 s[58:59], -1
	s_and_b64 vcc, exec, s[54:55]
	s_cbranch_vccz .LBB0_1536
	global_store_dword v[154:155], v156, off
	s_mov_b64 s[58:59], 0

.LBB0_1547:
	v_pk_mul_f32 v[146:147], v[154:155], v[154:155]
	v_pk_mul_f32 v[148:149], v[156:157], v[156:157]
	v_pk_mul_f32 v[152:153], v[158:159], v[158:159]
	v_pk_mul_f32 v[154:155], v[160:161], v[160:161]
	v_pk_mul_f32 v[150:151], v[150:151], v[150:151]
	v_pk_mul_f32 v[156:157], v[182:183], v[182:183]
	v_pk_mul_f32 v[158:159], v[184:185], v[184:185]
	v_pk_mul_f32 v[160:161], v[186:187], v[186:187]
	v_add_f32_e32 v158, v158, v159
	v_add_f32_e32 v160, v160, v161
	v_add_f32_e32 v156, v156, v157
	v_add_f32_e32 v150, v150, v151
	v_add_f32_e32 v151, v154, v155
	v_add_f32_e32 v152, v152, v153
	v_add_f32_e32 v148, v148, v149
	v_add_f32_e32 v146, v146, v147
	v_add_f32_e32 v158, v158, v160
	v_add_f32_e32 v150, v150, v156
	v_add_f32_e32 v151, v152, v151
	v_add_f32_e32 v146, v146, v148
	v_add_f32_e32 v150, v150, v158
	v_add_f32_e32 v146, v146, v151
	v_add_f32_e32 v146, v146, v150
	v_mov_b32_e32 v147, v146
	s_nop 1
	v_permlane16_swap_b32_e32 v146, v147
	s_mov_b64 s[56:57], s[36:37]
	s_waitcnt lgkmcnt(0)
	v_add_f32_e32 v146, v146, v147
	v_mov_b32_e32 v147, v146
	s_nop 1
	v_permlane32_swap_b32_e32 v146, v147
	s_and_saveexec_b64 s[54:55], s[12:13]
	s_cbranch_execz .LBB0_1553
	v_ashrrev_i32_e32 v179, 31, v178
	s_waitcnt lgkmcnt(0)
	v_add_f32_e32 v148, v146, v147
	v_lshlrev_b64 v[146:147], 6, v[178:179]
	v_lshl_add_u64 v[146:147], s[2:3], 0, v[146:147]
	v_lshl_add_u64 v[146:147], s[52:53], 2, v[146:147]
	s_lshl_b32 s26, s69, 2
	v_lshl_add_u64 v[146:147], v[146:147], 0, s[26:27]
	s_and_b64 vcc, exec, s[10:11]
	s_mov_b64 s[56:57], -1
	s_cbranch_vccnz .LBB0_1550
	s_mov_b64 s[56:57], 0
	global_store_dword v[146:147], v148, off

.LBB0_1561:
	v_pk_mul_f32 v[138:139], v[146:147], v[146:147]
	v_pk_mul_f32 v[140:141], v[148:149], v[148:149]
	v_pk_mul_f32 v[144:145], v[150:151], v[150:151]
	v_pk_mul_f32 v[146:147], v[152:153], v[152:153]
	v_pk_mul_f32 v[142:143], v[142:143], v[142:143]
	v_pk_mul_f32 v[148:149], v[154:155], v[154:155]
	v_pk_mul_f32 v[150:151], v[156:157], v[156:157]
	v_pk_mul_f32 v[152:153], v[158:159], v[158:159]
	v_add_f32_e32 v150, v150, v151
	v_add_f32_e32 v152, v152, v153
	v_add_f32_e32 v148, v148, v149
	v_add_f32_e32 v142, v142, v143
	v_add_f32_e32 v143, v146, v147
	v_add_f32_e32 v144, v144, v145
	v_add_f32_e32 v140, v140, v141
	v_add_f32_e32 v138, v138, v139
	v_add_f32_e32 v150, v150, v152
	v_add_f32_e32 v142, v142, v148
	v_add_f32_e32 v143, v144, v143
	v_add_f32_e32 v138, v138, v140
	v_add_f32_e32 v142, v142, v150
	v_add_f32_e32 v138, v138, v143
	v_add_f32_e32 v138, v138, v142
	v_mov_b32_e32 v139, v138
	s_nop 1
	v_permlane16_swap_b32_e32 v138, v139
	s_mov_b64 s[56:57], s[36:37]
	s_waitcnt lgkmcnt(0)
	v_add_f32_e32 v138, v138, v139
	v_mov_b32_e32 v139, v138
	s_nop 1
	v_permlane32_swap_b32_e32 v138, v139
	s_and_saveexec_b64 s[54:55], s[12:13]
	s_cbranch_execz .LBB0_1567
	v_ashrrev_i32_e32 v171, 31, v170
	s_waitcnt lgkmcnt(0)
	v_add_f32_e32 v140, v138, v139
	v_lshlrev_b64 v[138:139], 6, v[170:171]
	v_lshl_add_u64 v[138:139], s[2:3], 0, v[138:139]
	v_lshl_add_u64 v[138:139], s[52:53], 2, v[138:139]
	s_lshl_b32 s26, s69, 2
	v_lshl_add_u64 v[138:139], v[138:139], 0, s[26:27]
	s_and_b64 vcc, exec, s[10:11]
	s_mov_b64 s[56:57], -1
	s_cbranch_vccnz .LBB0_1564
	s_mov_b64 s[56:57], 0
	global_store_dword v[138:139], v140, off

.LBB0_1575:
	v_pk_mul_f32 v[130:131], v[138:139], v[138:139]
	v_pk_mul_f32 v[132:133], v[140:141], v[140:141]
	v_pk_mul_f32 v[136:137], v[142:143], v[142:143]
	v_pk_mul_f32 v[138:139], v[144:145], v[144:145]
	v_pk_mul_f32 v[134:135], v[134:135], v[134:135]
	v_pk_mul_f32 v[140:141], v[146:147], v[146:147]
	v_pk_mul_f32 v[142:143], v[148:149], v[148:149]
	v_pk_mul_f32 v[144:145], v[150:151], v[150:151]
	v_add_f32_e32 v142, v142, v143
	v_add_f32_e32 v144, v144, v145
	v_add_f32_e32 v140, v140, v141
	v_add_f32_e32 v134, v134, v135
	v_add_f32_e32 v135, v138, v139
	v_add_f32_e32 v136, v136, v137
	v_add_f32_e32 v132, v132, v133
	v_add_f32_e32 v130, v130, v131
	v_add_f32_e32 v142, v142, v144
	v_add_f32_e32 v134, v134, v140
	v_add_f32_e32 v135, v136, v135
	v_add_f32_e32 v130, v130, v132
	v_add_f32_e32 v134, v134, v142
	v_add_f32_e32 v130, v130, v135
	v_add_f32_e32 v130, v130, v134
	v_mov_b32_e32 v131, v130
	s_nop 1
	v_permlane16_swap_b32_e32 v130, v131
	s_waitcnt lgkmcnt(0)
	v_add_f32_e32 v130, v130, v131
	v_mov_b32_e32 v131, v130
	s_nop 1
	v_permlane32_swap_b32_e32 v130, v131
	s_and_saveexec_b64 s[54:55], s[12:13]
	s_cbranch_execz .LBB0_1580
	v_ashrrev_i32_e32 v165, 31, v164
	s_waitcnt lgkmcnt(0)
	v_add_f32_e32 v132, v130, v131
	v_lshlrev_b64 v[130:131], 6, v[164:165]
	v_lshl_add_u64 v[130:131], s[2:3], 0, v[130:131]
	v_lshl_add_u64 v[130:131], s[52:53], 2, v[130:131]
	s_lshl_b32 s26, s69, 2
	v_lshl_add_u64 v[130:131], v[130:131], 0, s[26:27]
	s_and_b64 vcc, exec, s[10:11]
	s_mov_b64 s[56:57], -1
	s_cbranch_vccnz .LBB0_1578
	s_mov_b64 s[56:57], 0
	global_store_dword v[130:131], v132, off

.LBB0_1588:
	v_pk_mul_f32 v[156:157], v[192:193], v[192:193]
	v_pk_mul_f32 v[160:161], v[202:203], v[202:203]
	v_pk_mul_f32 v[192:193], v[206:207], v[206:207]
	v_pk_mul_f32 v[202:203], v[208:209], v[208:209]
	v_pk_mul_f32 v[154:155], v[190:191], v[190:191]
	v_pk_mul_f32 v[190:191], v[204:205], v[204:205]
	v_pk_mul_f32 v[158:159], v[158:159], v[158:159]
	v_pk_mul_f32 v[188:189], v[188:189], v[188:189]
	v_add_f32_e32 v163, v202, v203
	v_add_f32_e32 v169, v192, v193
	v_add_f32_e32 v163, v169, v163
	v_add_f32_e32 v169, v188, v189
	v_add_f32_e32 v158, v158, v159
	v_add_f32_e32 v159, v190, v191
	v_add_f32_e32 v160, v160, v161
	v_add_f32_e32 v156, v156, v157
	v_add_f32_e32 v154, v154, v155
	v_add_f32_e32 v158, v158, v169
	v_add_f32_e32 v159, v160, v159
	v_add_f32_e32 v154, v154, v156
	v_add_f32_e32 v158, v158, v163
	v_add_f32_e32 v154, v154, v159
	v_add_f32_e32 v154, v154, v158
	v_mov_b32_e32 v155, v154
	s_nop 1
	v_permlane16_swap_b32_e32 v154, v155
	s_mov_b64 s[56:57], s[36:37]
	s_waitcnt lgkmcnt(0)
	v_add_f32_e32 v154, v154, v155
	v_mov_b32_e32 v155, v154
	s_nop 1
	v_permlane32_swap_b32_e32 v154, v155
	s_and_saveexec_b64 s[54:55], s[12:13]
	s_cbranch_execz .LBB0_1594
	v_ashrrev_i32_e32 v185, 31, v184
	s_waitcnt lgkmcnt(0)
	v_add_f32_e32 v156, v154, v155
	v_lshlrev_b64 v[154:155], 6, v[184:185]
	v_lshl_add_u64 v[154:155], s[2:3], 0, v[154:155]
	v_lshl_add_u64 v[154:155], s[52:53], 2, v[154:155]
	s_lshl_b32 s26, s69, 2
	v_lshl_add_u64 v[154:155], v[154:155], 0, s[26:27]
	s_and_b64 vcc, exec, s[10:11]
	s_mov_b64 s[56:57], -1
	s_cbranch_vccnz .LBB0_1591
	s_mov_b64 s[56:57], 0
	global_store_dword v[154:155], v156, off

.LBB0_1602:
	v_pk_mul_f32 v[146:147], v[154:155], v[154:155]
	v_pk_mul_f32 v[148:149], v[156:157], v[156:157]
	v_pk_mul_f32 v[152:153], v[158:159], v[158:159]
	v_pk_mul_f32 v[154:155], v[160:161], v[160:161]
	v_pk_mul_f32 v[150:151], v[150:151], v[150:151]
	v_pk_mul_f32 v[156:157], v[180:181], v[180:181]
	v_pk_mul_f32 v[158:159], v[182:183], v[182:183]
	v_pk_mul_f32 v[160:161], v[184:185], v[184:185]
	v_add_f32_e32 v158, v158, v159
	v_add_f32_e32 v160, v160, v161
	v_add_f32_e32 v156, v156, v157
	v_add_f32_e32 v150, v150, v151
	v_add_f32_e32 v151, v154, v155
	v_add_f32_e32 v152, v152, v153
	v_add_f32_e32 v148, v148, v149
	v_add_f32_e32 v146, v146, v147
	v_add_f32_e32 v158, v158, v160
	v_add_f32_e32 v150, v150, v156
	v_add_f32_e32 v151, v152, v151
	v_add_f32_e32 v146, v146, v148
	v_add_f32_e32 v150, v150, v158
	v_add_f32_e32 v146, v146, v151
	v_add_f32_e32 v146, v146, v150
	v_mov_b32_e32 v147, v146
	s_nop 1
	v_permlane16_swap_b32_e32 v146, v147
	s_mov_b64 s[56:57], s[36:37]
	s_waitcnt lgkmcnt(0)
	v_add_f32_e32 v146, v146, v147
	v_mov_b32_e32 v147, v146
	s_nop 1
	v_permlane32_swap_b32_e32 v146, v147
	s_and_saveexec_b64 s[54:55], s[12:13]
	s_cbranch_execz .LBB0_1608
	v_ashrrev_i32_e32 v177, 31, v176
	s_waitcnt lgkmcnt(0)
	v_add_f32_e32 v148, v146, v147
	v_lshlrev_b64 v[146:147], 6, v[176:177]
	v_lshl_add_u64 v[146:147], s[2:3], 0, v[146:147]
	v_lshl_add_u64 v[146:147], s[52:53], 2, v[146:147]
	s_lshl_b32 s26, s69, 2
	v_lshl_add_u64 v[146:147], v[146:147], 0, s[26:27]
	s_and_b64 vcc, exec, s[10:11]
	s_mov_b64 s[56:57], -1
	s_cbranch_vccnz .LBB0_1605
	s_mov_b64 s[56:57], 0
	global_store_dword v[146:147], v148, off

.LBB0_1616:
	v_pk_mul_f32 v[138:139], v[146:147], v[146:147]
	v_pk_mul_f32 v[140:141], v[148:149], v[148:149]
	v_pk_mul_f32 v[144:145], v[150:151], v[150:151]
	v_pk_mul_f32 v[146:147], v[152:153], v[152:153]
	v_pk_mul_f32 v[142:143], v[142:143], v[142:143]
	v_pk_mul_f32 v[148:149], v[154:155], v[154:155]
	v_pk_mul_f32 v[150:151], v[156:157], v[156:157]
	v_pk_mul_f32 v[152:153], v[158:159], v[158:159]
	v_add_f32_e32 v150, v150, v151
	v_add_f32_e32 v152, v152, v153
	v_add_f32_e32 v148, v148, v149
	v_add_f32_e32 v142, v142, v143
	v_add_f32_e32 v143, v146, v147
	v_add_f32_e32 v144, v144, v145
	v_add_f32_e32 v140, v140, v141
	v_add_f32_e32 v138, v138, v139
	v_add_f32_e32 v150, v150, v152
	v_add_f32_e32 v142, v142, v148
	v_add_f32_e32 v143, v144, v143
	v_add_f32_e32 v138, v138, v140
	v_add_f32_e32 v142, v142, v150
	v_add_f32_e32 v138, v138, v143
	v_add_f32_e32 v138, v138, v142
	v_mov_b32_e32 v139, v138
	s_nop 1
	v_permlane16_swap_b32_e32 v138, v139
	s_mov_b64 s[56:57], s[36:37]
	s_waitcnt lgkmcnt(0)
	v_add_f32_e32 v138, v138, v139
	v_mov_b32_e32 v139, v138
	s_nop 1
	v_permlane32_swap_b32_e32 v138, v139
	s_and_saveexec_b64 s[54:55], s[12:13]
	s_cbranch_execz .LBB0_1622
	v_ashrrev_i32_e32 v169, 31, v168
	s_waitcnt lgkmcnt(0)
	v_add_f32_e32 v140, v138, v139
	v_lshlrev_b64 v[138:139], 6, v[168:169]
	v_lshl_add_u64 v[138:139], s[2:3], 0, v[138:139]
	v_lshl_add_u64 v[138:139], s[52:53], 2, v[138:139]
	s_lshl_b32 s26, s69, 2
	v_lshl_add_u64 v[138:139], v[138:139], 0, s[26:27]
	s_and_b64 vcc, exec, s[10:11]
	s_mov_b64 s[56:57], -1
	s_cbranch_vccnz .LBB0_1619
	s_mov_b64 s[56:57], 0
	global_store_dword v[138:139], v140, off

.LBB0_1630:
	v_pk_mul_f32 v[130:131], v[138:139], v[138:139]
	v_pk_mul_f32 v[132:133], v[140:141], v[140:141]
	v_pk_mul_f32 v[136:137], v[142:143], v[142:143]
	v_pk_mul_f32 v[138:139], v[144:145], v[144:145]
	v_pk_mul_f32 v[134:135], v[134:135], v[134:135]
	v_pk_mul_f32 v[140:141], v[146:147], v[146:147]
	v_pk_mul_f32 v[142:143], v[148:149], v[148:149]
	v_pk_mul_f32 v[144:145], v[150:151], v[150:151]
	v_add_f32_e32 v142, v142, v143
	v_add_f32_e32 v144, v144, v145
	v_add_f32_e32 v140, v140, v141
	v_add_f32_e32 v134, v134, v135
	v_add_f32_e32 v135, v138, v139
	v_add_f32_e32 v136, v136, v137
	v_add_f32_e32 v132, v132, v133
	v_add_f32_e32 v130, v130, v131
	v_add_f32_e32 v142, v142, v144
	v_add_f32_e32 v134, v134, v140
	v_add_f32_e32 v135, v136, v135
	v_add_f32_e32 v130, v130, v132
	v_add_f32_e32 v134, v134, v142
	v_add_f32_e32 v130, v130, v135
	v_add_f32_e32 v130, v130, v134
	v_mov_b32_e32 v131, v130
	s_nop 1
	v_permlane16_swap_b32_e32 v130, v131
	s_waitcnt lgkmcnt(0)
	v_add_f32_e32 v130, v130, v131
	v_mov_b32_e32 v131, v130
	s_nop 1
	v_permlane32_swap_b32_e32 v130, v131
	s_and_saveexec_b64 s[50:51], s[12:13]
	s_cbranch_execz .LBB0_1635
	v_ashrrev_i32_e32 v163, 31, v162
	s_waitcnt lgkmcnt(0)
	v_add_f32_e32 v132, v130, v131
	v_lshlrev_b64 v[130:131], 6, v[162:163]
	v_lshl_add_u64 v[130:131], s[2:3], 0, v[130:131]
	v_lshl_add_u64 v[130:131], s[52:53], 2, v[130:131]
	s_lshl_b32 s26, s69, 2
	v_lshl_add_u64 v[130:131], v[130:131], 0, s[26:27]
	s_and_b64 vcc, exec, s[10:11]
	s_mov_b64 s[10:11], -1
	s_cbranch_vccnz .LBB0_1633
	s_mov_b64 s[10:11], 0
	global_store_dword v[130:131], v132, off

.LBB0_1932:
	v_pk_mul_f32 v[118:119], v[130:131], v[130:131]
	v_pk_mul_f32 v[120:121], v[132:133], v[132:133]
	v_pk_mul_f32 v[122:123], v[122:123], v[122:123]
	v_pk_mul_f32 v[124:125], v[124:125], v[124:125]
	v_add_f32_e32 v120, v120, v121
	v_add_f32_e32 v118, v118, v119
	v_pk_mul_f32 v[126:127], v[190:191], v[190:191]
	v_pk_mul_f32 v[130:131], v[192:193], v[192:193]
	v_pk_mul_f32 v[128:129], v[128:129], v[128:129]
	v_pk_mul_f32 v[132:133], v[154:155], v[154:155]
	v_add_f32_e32 v124, v124, v125
	v_add_f32_e32 v122, v122, v123
	v_add_f32_e32 v118, v118, v120
	v_and_b32_e32 v120, 64, v207
	v_add_f32_e32 v132, v132, v133
	v_add_f32_e32 v128, v128, v129
	v_add_f32_e32 v122, v122, v124
	v_add_f32_e32 v123, v130, v131
	v_add_f32_e32 v124, v126, v127
	v_xor_b32_e32 v119, 16, v207
	v_add_u32_e32 v120, 64, v120
	v_add_f32_e32 v128, v128, v132
	v_add_f32_e32 v123, v124, v123
	v_cmp_lt_i32_e32 vcc, v119, v120
	v_add_f32_e32 v122, v122, v128
	v_add_f32_e32 v118, v118, v123
	v_cndmask_b32_e32 v119, v207, v119, vcc
	v_add_f32_e32 v118, v118, v122
	v_lshlrev_b32_e32 v128, 2, v119
	v_mov_b32_e32 v119, v118
	s_nop 1
	v_permlane16_swap_b32_e32 v118, v119
	s_lshl_b32 s44, s12, 2
	v_cmp_eq_u32_e64 s[10:11], 0, v163
	s_ashr_i32 s45, s44, 31
	s_mov_b64 s[50:51], s[36:37]
	s_waitcnt lgkmcnt(0)
	v_add_f32_e32 v118, v118, v119
	v_xor_b32_e32 v119, 32, v207
	v_cmp_lt_i32_e32 vcc, v119, v120
	s_nop 1
	v_cndmask_b32_e32 v119, v207, v119, vcc
	v_lshlrev_b32_e32 v129, 2, v119
	v_mov_b32_e32 v119, v118
	s_nop 1
	v_permlane32_swap_b32_e32 v118, v119
	s_and_saveexec_b64 s[48:49], s[10:11]
	s_cbranch_execz .LBB0_1938
	v_ashrrev_i32_e32 v163, 31, v162
	s_waitcnt lgkmcnt(0)
	v_add_f32_e32 v120, v118, v119
	v_lshlrev_b64 v[118:119], 6, v[162:163]
	v_lshl_add_u64 v[118:119], s[2:3], 0, v[118:119]
	v_lshl_add_u64 v[118:119], s[44:45], 2, v[118:119]
	s_lshl_b32 s20, s59, 2
	v_lshl_add_u64 v[118:119], v[118:119], 0, s[20:21]
	s_mov_b64 s[50:51], -1
	s_and_b64 vcc, exec, s[46:47]
	s_cbranch_vccz .LBB0_1935
	global_store_dword v[118:119], v120, off
	s_mov_b64 s[50:51], 0

.LBB0_1946:
	v_pk_mul_f32 v[102:103], v[102:103], v[102:103]
	v_pk_mul_f32 v[104:105], v[104:105], v[104:105]
	v_pk_mul_f32 v[98:99], v[110:111], v[110:111]
	v_pk_mul_f32 v[100:101], v[112:113], v[112:113]
	v_pk_mul_f32 v[106:107], v[118:119], v[118:119]
	v_pk_mul_f32 v[110:111], v[120:121], v[120:121]
	v_pk_mul_f32 v[108:109], v[108:109], v[108:109]
	v_pk_mul_f32 v[112:113], v[122:123], v[122:123]
	v_add_f32_e32 v104, v104, v105
	v_add_f32_e32 v102, v102, v103
	v_add_f32_e32 v112, v112, v113
	v_add_f32_e32 v108, v108, v109
	v_add_f32_e32 v102, v102, v104
	v_add_f32_e32 v103, v110, v111
	v_add_f32_e32 v104, v106, v107
	v_add_f32_e32 v100, v100, v101
	v_add_f32_e32 v98, v98, v99
	v_add_f32_e32 v108, v108, v112
	v_add_f32_e32 v103, v104, v103
	v_add_f32_e32 v98, v98, v100
	v_add_f32_e32 v102, v102, v108
	v_add_f32_e32 v98, v98, v103
	v_add_f32_e32 v98, v98, v102
	v_mov_b32_e32 v99, v98
	s_nop 1
	v_permlane16_swap_b32_e32 v98, v99
	s_mov_b64 s[48:49], s[36:37]
	s_waitcnt lgkmcnt(0)
	v_add_f32_e32 v98, v98, v99
	v_mov_b32_e32 v99, v98
	s_nop 1
	v_permlane32_swap_b32_e32 v98, v99
	s_and_saveexec_b64 s[46:47], s[10:11]
	s_cbranch_execz .LBB0_1952
	v_ashrrev_i32_e32 v179, 31, v178
	s_waitcnt lgkmcnt(0)
	v_add_f32_e32 v100, v98, v99
	v_lshlrev_b64 v[98:99], 6, v[178:179]
	v_lshl_add_u64 v[98:99], s[2:3], 0, v[98:99]
	v_lshl_add_u64 v[98:99], s[44:45], 2, v[98:99]
	s_lshl_b32 s20, s59, 2
	v_lshl_add_u64 v[98:99], v[98:99], 0, s[20:21]
	s_and_b64 vcc, exec, s[6:7]
	s_mov_b64 s[48:49], -1
	s_cbranch_vccnz .LBB0_1949
	s_mov_b64 s[48:49], 0
	global_store_dword v[98:99], v100, off

.LBB0_1960:
	v_pk_mul_f32 v[86:87], v[86:87], v[86:87]
	v_pk_mul_f32 v[88:89], v[88:89], v[88:89]
	v_pk_mul_f32 v[82:83], v[94:95], v[94:95]
	v_pk_mul_f32 v[84:85], v[96:97], v[96:97]
	v_pk_mul_f32 v[90:91], v[98:99], v[98:99]
	v_pk_mul_f32 v[94:95], v[100:101], v[100:101]
	v_pk_mul_f32 v[92:93], v[92:93], v[92:93]
	v_pk_mul_f32 v[96:97], v[102:103], v[102:103]
	v_add_f32_e32 v88, v88, v89
	v_add_f32_e32 v86, v86, v87
	v_add_f32_e32 v96, v96, v97
	v_add_f32_e32 v92, v92, v93
	v_add_f32_e32 v86, v86, v88
	v_add_f32_e32 v87, v94, v95
	v_add_f32_e32 v88, v90, v91
	v_add_f32_e32 v84, v84, v85
	v_add_f32_e32 v82, v82, v83
	v_add_f32_e32 v92, v92, v96
	v_add_f32_e32 v87, v88, v87
	v_add_f32_e32 v82, v82, v84
	v_add_f32_e32 v86, v86, v92
	v_add_f32_e32 v82, v82, v87
	v_add_f32_e32 v82, v82, v86
	v_mov_b32_e32 v83, v82
	s_nop 1
	v_permlane16_swap_b32_e32 v82, v83
	s_mov_b64 s[48:49], s[36:37]
	s_waitcnt lgkmcnt(0)
	v_add_f32_e32 v82, v82, v83
	v_mov_b32_e32 v83, v82
	s_nop 1
	v_permlane32_swap_b32_e32 v82, v83
	s_and_saveexec_b64 s[46:47], s[10:11]
	s_cbranch_execz .LBB0_1966
	v_ashrrev_i32_e32 v171, 31, v170
	s_waitcnt lgkmcnt(0)
	v_add_f32_e32 v84, v82, v83
	v_lshlrev_b64 v[82:83], 6, v[170:171]
	v_lshl_add_u64 v[82:83], s[2:3], 0, v[82:83]
	v_lshl_add_u64 v[82:83], s[44:45], 2, v[82:83]
	s_lshl_b32 s20, s59, 2
	v_lshl_add_u64 v[82:83], v[82:83], 0, s[20:21]
	s_and_b64 vcc, exec, s[6:7]
	s_mov_b64 s[48:49], -1
	s_cbranch_vccnz .LBB0_1963
	s_mov_b64 s[48:49], 0
	global_store_dword v[82:83], v84, off

.LBB0_1974:
	v_pk_mul_f32 v[70:71], v[70:71], v[70:71]
	v_pk_mul_f32 v[72:73], v[72:73], v[72:73]
	v_pk_mul_f32 v[66:67], v[78:79], v[78:79]
	v_pk_mul_f32 v[68:69], v[80:81], v[80:81]
	v_pk_mul_f32 v[74:75], v[82:83], v[82:83]
	v_pk_mul_f32 v[78:79], v[84:85], v[84:85]
	v_pk_mul_f32 v[76:77], v[76:77], v[76:77]
	v_pk_mul_f32 v[80:81], v[86:87], v[86:87]
	v_add_f32_e32 v72, v72, v73
	v_add_f32_e32 v70, v70, v71
	v_add_f32_e32 v80, v80, v81
	v_add_f32_e32 v76, v76, v77
	v_add_f32_e32 v70, v70, v72
	v_add_f32_e32 v71, v78, v79
	v_add_f32_e32 v72, v74, v75
	v_add_f32_e32 v68, v68, v69
	v_add_f32_e32 v66, v66, v67
	v_add_f32_e32 v76, v76, v80
	v_add_f32_e32 v71, v72, v71
	v_add_f32_e32 v66, v66, v68
	v_add_f32_e32 v70, v70, v76
	v_add_f32_e32 v66, v66, v71
	v_add_f32_e32 v66, v66, v70
	v_mov_b32_e32 v67, v66
	s_nop 1
	v_permlane16_swap_b32_e32 v66, v67
	s_waitcnt lgkmcnt(0)
	v_add_f32_e32 v66, v66, v67
	v_mov_b32_e32 v67, v66
	s_nop 1
	v_permlane32_swap_b32_e32 v66, v67
	s_and_saveexec_b64 s[46:47], s[10:11]
	s_cbranch_execz .LBB0_1979
	v_ashrrev_i32_e32 v165, 31, v164
	s_waitcnt lgkmcnt(0)
	v_add_f32_e32 v68, v66, v67
	v_lshlrev_b64 v[66:67], 6, v[164:165]
	v_lshl_add_u64 v[66:67], s[2:3], 0, v[66:67]
	v_lshl_add_u64 v[66:67], s[44:45], 2, v[66:67]
	s_lshl_b32 s20, s59, 2
	v_lshl_add_u64 v[66:67], v[66:67], 0, s[20:21]
	s_and_b64 vcc, exec, s[6:7]
	s_mov_b64 s[48:49], -1
	s_cbranch_vccnz .LBB0_1977
	s_mov_b64 s[48:49], 0
	global_store_dword v[66:67], v68, off

.LBB0_1987:
	v_pk_mul_f32 v[54:55], v[54:55], v[54:55]
	v_pk_mul_f32 v[56:57], v[56:57], v[56:57]
	v_pk_mul_f32 v[50:51], v[62:63], v[62:63]
	v_pk_mul_f32 v[52:53], v[64:65], v[64:65]
	v_pk_mul_f32 v[58:59], v[122:123], v[122:123]
	v_pk_mul_f32 v[62:63], v[124:125], v[124:125]
	v_pk_mul_f32 v[60:61], v[60:61], v[60:61]
	v_pk_mul_f32 v[64:65], v[90:91], v[90:91]
	v_add_f32_e32 v56, v56, v57
	v_add_f32_e32 v54, v54, v55
	v_add_f32_e32 v64, v64, v65
	v_add_f32_e32 v60, v60, v61
	v_add_f32_e32 v54, v54, v56
	v_add_f32_e32 v55, v62, v63
	v_add_f32_e32 v56, v58, v59
	v_add_f32_e32 v52, v52, v53
	v_add_f32_e32 v50, v50, v51
	v_add_f32_e32 v60, v60, v64
	v_add_f32_e32 v55, v56, v55
	v_add_f32_e32 v50, v50, v52
	v_add_f32_e32 v54, v54, v60
	v_add_f32_e32 v50, v50, v55
	v_add_f32_e32 v50, v50, v54
	v_mov_b32_e32 v51, v50
	s_nop 1
	v_permlane16_swap_b32_e32 v50, v51
	s_mov_b64 s[48:49], s[36:37]
	s_waitcnt lgkmcnt(0)
	v_add_f32_e32 v50, v50, v51
	v_mov_b32_e32 v51, v50
	s_nop 1
	v_permlane32_swap_b32_e32 v50, v51
	s_and_saveexec_b64 s[46:47], s[10:11]
	s_cbranch_execz .LBB0_1993
	v_ashrrev_i32_e32 v117, 31, v116
	s_waitcnt lgkmcnt(0)
	v_add_f32_e32 v52, v50, v51
	v_lshlrev_b64 v[50:51], 6, v[116:117]
	v_lshl_add_u64 v[50:51], s[2:3], 0, v[50:51]
	v_lshl_add_u64 v[50:51], s[44:45], 2, v[50:51]
	s_lshl_b32 s20, s59, 2
	v_lshl_add_u64 v[50:51], v[50:51], 0, s[20:21]
	s_and_b64 vcc, exec, s[6:7]
	s_mov_b64 s[48:49], -1
	s_cbranch_vccnz .LBB0_1990
	s_mov_b64 s[48:49], 0
	global_store_dword v[50:51], v52, off

.LBB0_2001:
	v_pk_mul_f32 v[38:39], v[38:39], v[38:39]
	v_pk_mul_f32 v[40:41], v[40:41], v[40:41]
	v_pk_mul_f32 v[34:35], v[46:47], v[46:47]
	v_pk_mul_f32 v[36:37], v[48:49], v[48:49]
	v_pk_mul_f32 v[42:43], v[50:51], v[50:51]
	v_pk_mul_f32 v[46:47], v[52:53], v[52:53]
	v_pk_mul_f32 v[44:45], v[44:45], v[44:45]
	v_pk_mul_f32 v[48:49], v[54:55], v[54:55]
	v_add_f32_e32 v40, v40, v41
	v_add_f32_e32 v38, v38, v39
	v_add_f32_e32 v48, v48, v49
	v_add_f32_e32 v44, v44, v45
	v_add_f32_e32 v38, v38, v40
	v_add_f32_e32 v39, v46, v47
	v_add_f32_e32 v40, v42, v43
	v_add_f32_e32 v36, v36, v37
	v_add_f32_e32 v34, v34, v35
	v_add_f32_e32 v44, v44, v48
	v_add_f32_e32 v39, v40, v39
	v_add_f32_e32 v34, v34, v36
	v_add_f32_e32 v38, v38, v44
	v_add_f32_e32 v34, v34, v39
	v_add_f32_e32 v34, v34, v38
	v_mov_b32_e32 v35, v34
	s_nop 1
	v_permlane16_swap_b32_e32 v34, v35
	s_mov_b64 s[48:49], s[36:37]
	s_waitcnt lgkmcnt(0)
	v_add_f32_e32 v34, v34, v35
	v_mov_b32_e32 v35, v34
	s_nop 1
	v_permlane32_swap_b32_e32 v34, v35
	s_and_saveexec_b64 s[46:47], s[10:11]
	s_cbranch_execz .LBB0_2007
	v_ashrrev_i32_e32 v109, 31, v108
	s_waitcnt lgkmcnt(0)
	v_add_f32_e32 v36, v34, v35
	v_lshlrev_b64 v[34:35], 6, v[108:109]
	v_lshl_add_u64 v[34:35], s[2:3], 0, v[34:35]
	v_lshl_add_u64 v[34:35], s[44:45], 2, v[34:35]
	s_lshl_b32 s20, s59, 2
	v_lshl_add_u64 v[34:35], v[34:35], 0, s[20:21]
	s_and_b64 vcc, exec, s[6:7]
	s_mov_b64 s[48:49], -1
	s_cbranch_vccnz .LBB0_2004
	s_mov_b64 s[48:49], 0
	global_store_dword v[34:35], v36, off

.LBB0_2015:
	v_pk_mul_f32 v[22:23], v[22:23], v[22:23]
	v_pk_mul_f32 v[24:25], v[24:25], v[24:25]
	v_pk_mul_f32 v[18:19], v[30:31], v[30:31]
	v_pk_mul_f32 v[20:21], v[32:33], v[32:33]
	v_pk_mul_f32 v[26:27], v[34:35], v[34:35]
	v_pk_mul_f32 v[30:31], v[36:37], v[36:37]
	v_pk_mul_f32 v[28:29], v[28:29], v[28:29]
	v_pk_mul_f32 v[32:33], v[38:39], v[38:39]
	v_add_f32_e32 v24, v24, v25
	v_add_f32_e32 v22, v22, v23
	v_add_f32_e32 v32, v32, v33
	v_add_f32_e32 v28, v28, v29
	v_add_f32_e32 v22, v22, v24
	v_add_f32_e32 v23, v30, v31
	v_add_f32_e32 v24, v26, v27
	v_add_f32_e32 v20, v20, v21
	v_add_f32_e32 v18, v18, v19
	v_add_f32_e32 v28, v28, v32
	v_add_f32_e32 v23, v24, v23
	v_add_f32_e32 v18, v18, v20
	v_add_f32_e32 v22, v22, v28
	v_add_f32_e32 v18, v18, v23
	v_add_f32_e32 v18, v18, v22
	v_mov_b32_e32 v19, v18
	s_nop 1
	v_permlane16_swap_b32_e32 v18, v19
	s_mov_b64 s[48:49], s[36:37]
	s_waitcnt lgkmcnt(0)
	v_add_f32_e32 v18, v18, v19
	v_mov_b32_e32 v19, v18
	s_nop 1
	v_permlane32_swap_b32_e32 v18, v19
	s_and_saveexec_b64 s[46:47], s[10:11]
	s_cbranch_execz .LBB0_2021
	v_ashrrev_i32_e32 v101, 31, v100
	s_waitcnt lgkmcnt(0)
	v_add_f32_e32 v20, v18, v19
	v_lshlrev_b64 v[18:19], 6, v[100:101]
	v_lshl_add_u64 v[18:19], s[2:3], 0, v[18:19]
	v_lshl_add_u64 v[18:19], s[44:45], 2, v[18:19]
	s_lshl_b32 s20, s59, 2
	v_lshl_add_u64 v[18:19], v[18:19], 0, s[20:21]
	s_and_b64 vcc, exec, s[6:7]
	s_mov_b64 s[48:49], -1
	s_cbranch_vccnz .LBB0_2018
	s_mov_b64 s[48:49], 0
	global_store_dword v[18:19], v20, off

.LBB0_2029:
	v_pk_mul_f32 v[6:7], v[6:7], v[6:7]
	v_pk_mul_f32 v[8:9], v[8:9], v[8:9]
	v_pk_mul_f32 v[2:3], v[14:15], v[14:15]
	v_pk_mul_f32 v[4:5], v[16:17], v[16:17]
	v_pk_mul_f32 v[10:11], v[18:19], v[18:19]
	v_pk_mul_f32 v[14:15], v[20:21], v[20:21]
	v_pk_mul_f32 v[12:13], v[12:13], v[12:13]
	v_pk_mul_f32 v[16:17], v[22:23], v[22:23]
	v_add_f32_e32 v8, v8, v9
	v_add_f32_e32 v6, v6, v7
	v_add_f32_e32 v16, v16, v17
	v_add_f32_e32 v12, v12, v13
	v_add_f32_e32 v6, v6, v8
	v_add_f32_e32 v7, v14, v15
	v_add_f32_e32 v8, v10, v11
	v_add_f32_e32 v4, v4, v5
	v_add_f32_e32 v2, v2, v3
	v_add_f32_e32 v12, v12, v16
	v_add_f32_e32 v7, v8, v7
	v_add_f32_e32 v2, v2, v4
	v_add_f32_e32 v6, v6, v12
	v_add_f32_e32 v2, v2, v7
	v_add_f32_e32 v2, v2, v6
	v_mov_b32_e32 v3, v2
	s_nop 1
	v_permlane16_swap_b32_e32 v2, v3
	s_waitcnt lgkmcnt(0)
	v_add_f32_e32 v2, v2, v3
	v_mov_b32_e32 v3, v2
	s_nop 1
	v_permlane32_swap_b32_e32 v2, v3
	s_and_saveexec_b64 s[42:43], s[10:11]
	s_cbranch_execz .LBB0_2034
	v_ashrrev_i32_e32 v95, 31, v94
	s_waitcnt lgkmcnt(0)
	v_add_f32_e32 v4, v2, v3
	v_lshlrev_b64 v[2:3], 6, v[94:95]
	v_lshl_add_u64 v[2:3], s[2:3], 0, v[2:3]
	v_lshl_add_u64 v[2:3], s[44:45], 2, v[2:3]
	s_lshl_b32 s20, s59, 2
	v_lshl_add_u64 v[2:3], v[2:3], 0, s[20:21]
	s_and_b64 vcc, exec, s[6:7]
	s_mov_b64 s[6:7], -1
	s_cbranch_vccnz .LBB0_2032
	s_mov_b64 s[6:7], 0
	global_store_dword v[2:3], v4, off

.LBB0_2243:
	v_pk_mul_f32 v[154:155], v[190:191], v[190:191]
	v_pk_mul_f32 v[156:157], v[192:193], v[192:193]
	v_pk_mul_f32 v[160:161], v[200:201], v[200:201]
	v_pk_mul_f32 v[192:193], v[204:205], v[204:205]
	v_pk_mul_f32 v[200:201], v[206:207], v[206:207]
	v_add_f32_e32 v156, v156, v157
	v_add_f32_e32 v154, v154, v155
	v_pk_mul_f32 v[190:191], v[202:203], v[202:203]
	v_pk_mul_f32 v[158:159], v[158:159], v[158:159]
	v_pk_mul_f32 v[188:189], v[188:189], v[188:189]
	v_add_f32_e32 v165, v200, v201
	v_add_f32_e32 v171, v192, v193
	v_add_f32_e32 v154, v154, v156
	v_and_b32_e32 v156, 64, v213
	v_add_f32_e32 v165, v171, v165
	v_add_f32_e32 v171, v188, v189
	v_add_f32_e32 v158, v158, v159
	v_add_f32_e32 v159, v190, v191
	v_add_f32_e32 v160, v160, v161
	v_xor_b32_e32 v155, 16, v213
	v_add_u32_e32 v156, 64, v156
	v_add_f32_e32 v158, v158, v171
	v_add_f32_e32 v159, v160, v159
	v_cmp_lt_i32_e32 vcc, v155, v156
	v_add_f32_e32 v158, v158, v165
	v_add_f32_e32 v154, v154, v159
	v_cndmask_b32_e32 v155, v213, v155, vcc
	v_add_f32_e32 v154, v154, v158
	v_lshlrev_b32_e32 v216, 2, v155
	v_mov_b32_e32 v155, v154
	s_nop 1
	v_permlane16_swap_b32_e32 v154, v155
	s_lshl_b32 s40, s48, 2
	v_cmp_eq_u32_e64 s[14:15], 0, v163
	s_ashr_i32 s41, s40, 31
	s_mov_b64 s[46:47], s[36:37]
	s_waitcnt lgkmcnt(0)
	v_add_f32_e32 v154, v154, v155
	v_xor_b32_e32 v155, 32, v213
	v_cmp_lt_i32_e32 vcc, v155, v156
	s_nop 1
	v_cndmask_b32_e32 v155, v213, v155, vcc
	v_lshlrev_b32_e32 v217, 2, v155
	v_mov_b32_e32 v155, v154
	s_nop 1
	v_permlane32_swap_b32_e32 v154, v155
	s_and_saveexec_b64 s[44:45], s[14:15]
	s_cbranch_execz .LBB0_2249
	v_ashrrev_i32_e32 v163, 31, v162
	s_waitcnt lgkmcnt(0)
	v_add_f32_e32 v156, v154, v155
	v_lshlrev_b64 v[154:155], 6, v[162:163]
	v_lshl_add_u64 v[154:155], s[88:89], 0, v[154:155]
	v_lshl_add_u64 v[154:155], s[40:41], 2, v[154:155]
	s_lshl_b32 s22, s60, 2
	v_lshl_add_u64 v[154:155], v[154:155], 0, s[22:23]
	s_mov_b64 s[46:47], -1
	s_and_b64 vcc, exec, s[42:43]
	s_cbranch_vccz .LBB0_2246
	global_store_dword v[154:155], v156, off
	s_mov_b64 s[46:47], 0

.LBB0_2257:
	v_pk_mul_f32 v[146:147], v[154:155], v[154:155]
	v_pk_mul_f32 v[148:149], v[156:157], v[156:157]
	v_pk_mul_f32 v[150:151], v[158:159], v[158:159]
	v_pk_mul_f32 v[154:155], v[160:161], v[160:161]
	v_pk_mul_f32 v[152:153], v[152:153], v[152:153]
	v_pk_mul_f32 v[156:157], v[182:183], v[182:183]
	v_pk_mul_f32 v[158:159], v[184:185], v[184:185]
	v_pk_mul_f32 v[160:161], v[186:187], v[186:187]
	v_add_f32_e32 v158, v158, v159
	v_add_f32_e32 v160, v160, v161
	v_add_f32_e32 v156, v156, v157
	v_add_f32_e32 v152, v152, v153
	v_add_f32_e32 v153, v154, v155
	v_add_f32_e32 v150, v150, v151
	v_add_f32_e32 v148, v148, v149
	v_add_f32_e32 v146, v146, v147
	v_add_f32_e32 v158, v158, v160
	v_add_f32_e32 v152, v152, v156
	v_add_f32_e32 v150, v150, v153
	v_add_f32_e32 v146, v146, v148
	v_add_f32_e32 v152, v152, v158
	v_add_f32_e32 v146, v146, v150
	v_add_f32_e32 v146, v146, v152
	v_mov_b32_e32 v147, v146
	s_nop 1
	v_permlane16_swap_b32_e32 v146, v147
	s_mov_b64 s[44:45], s[36:37]
	s_waitcnt lgkmcnt(0)
	v_add_f32_e32 v146, v146, v147
	v_mov_b32_e32 v147, v146
	s_nop 1
	v_permlane32_swap_b32_e32 v146, v147
	s_and_saveexec_b64 s[42:43], s[14:15]
	s_cbranch_execz .LBB0_2263
	v_ashrrev_i32_e32 v179, 31, v178
	s_waitcnt lgkmcnt(0)
	v_add_f32_e32 v148, v146, v147
	v_lshlrev_b64 v[146:147], 6, v[178:179]
	v_lshl_add_u64 v[146:147], s[88:89], 0, v[146:147]
	v_lshl_add_u64 v[146:147], s[40:41], 2, v[146:147]
	s_lshl_b32 s22, s60, 2
	v_lshl_add_u64 v[146:147], v[146:147], 0, s[22:23]
	s_and_b64 vcc, exec, s[12:13]
	s_mov_b64 s[44:45], -1
	s_cbranch_vccnz .LBB0_2260
	s_mov_b64 s[44:45], 0
	global_store_dword v[146:147], v148, off

.LBB0_2271:
	v_pk_mul_f32 v[138:139], v[146:147], v[146:147]
	v_pk_mul_f32 v[140:141], v[148:149], v[148:149]
	v_pk_mul_f32 v[142:143], v[150:151], v[150:151]
	v_pk_mul_f32 v[146:147], v[152:153], v[152:153]
	v_pk_mul_f32 v[144:145], v[144:145], v[144:145]
	v_pk_mul_f32 v[148:149], v[154:155], v[154:155]
	v_pk_mul_f32 v[150:151], v[156:157], v[156:157]
	v_pk_mul_f32 v[152:153], v[158:159], v[158:159]
	v_add_f32_e32 v150, v150, v151
	v_add_f32_e32 v152, v152, v153
	v_add_f32_e32 v148, v148, v149
	v_add_f32_e32 v144, v144, v145
	v_add_f32_e32 v145, v146, v147
	v_add_f32_e32 v142, v142, v143
	v_add_f32_e32 v140, v140, v141
	v_add_f32_e32 v138, v138, v139
	v_add_f32_e32 v150, v150, v152
	v_add_f32_e32 v144, v144, v148
	v_add_f32_e32 v142, v142, v145
	v_add_f32_e32 v138, v138, v140
	v_add_f32_e32 v144, v144, v150
	v_add_f32_e32 v138, v138, v142
	v_add_f32_e32 v138, v138, v144
	v_mov_b32_e32 v139, v138
	s_nop 1
	v_permlane16_swap_b32_e32 v138, v139
	s_mov_b64 s[44:45], s[36:37]
	s_waitcnt lgkmcnt(0)
	v_add_f32_e32 v138, v138, v139
	v_mov_b32_e32 v139, v138
	s_nop 1
	v_permlane32_swap_b32_e32 v138, v139
	s_and_saveexec_b64 s[42:43], s[14:15]
	s_cbranch_execz .LBB0_2277
	v_ashrrev_i32_e32 v171, 31, v170
	s_waitcnt lgkmcnt(0)
	v_add_f32_e32 v140, v138, v139
	v_lshlrev_b64 v[138:139], 6, v[170:171]
	v_lshl_add_u64 v[138:139], s[88:89], 0, v[138:139]
	v_lshl_add_u64 v[138:139], s[40:41], 2, v[138:139]
	s_lshl_b32 s22, s60, 2
	v_lshl_add_u64 v[138:139], v[138:139], 0, s[22:23]
	s_and_b64 vcc, exec, s[12:13]
	s_mov_b64 s[44:45], -1
	s_cbranch_vccnz .LBB0_2274
	s_mov_b64 s[44:45], 0
	global_store_dword v[138:139], v140, off

.LBB0_2285:
	v_pk_mul_f32 v[130:131], v[138:139], v[138:139]
	v_pk_mul_f32 v[132:133], v[140:141], v[140:141]
	v_pk_mul_f32 v[134:135], v[142:143], v[142:143]
	v_pk_mul_f32 v[138:139], v[144:145], v[144:145]
	v_pk_mul_f32 v[136:137], v[136:137], v[136:137]
	v_pk_mul_f32 v[140:141], v[146:147], v[146:147]
	v_pk_mul_f32 v[142:143], v[148:149], v[148:149]
	v_pk_mul_f32 v[144:145], v[150:151], v[150:151]
	v_add_f32_e32 v142, v142, v143
	v_add_f32_e32 v144, v144, v145
	v_add_f32_e32 v140, v140, v141
	v_add_f32_e32 v136, v136, v137
	v_add_f32_e32 v137, v138, v139
	v_add_f32_e32 v134, v134, v135
	v_add_f32_e32 v132, v132, v133
	v_add_f32_e32 v130, v130, v131
	v_add_f32_e32 v142, v142, v144
	v_add_f32_e32 v136, v136, v140
	v_add_f32_e32 v134, v134, v137
	v_add_f32_e32 v130, v130, v132
	v_add_f32_e32 v136, v136, v142
	v_add_f32_e32 v130, v130, v134
	v_add_f32_e32 v130, v130, v136
	v_mov_b32_e32 v131, v130
	s_nop 1
	v_permlane16_swap_b32_e32 v130, v131
	s_waitcnt lgkmcnt(0)
	v_add_f32_e32 v130, v130, v131
	v_mov_b32_e32 v131, v130
	s_nop 1
	v_permlane32_swap_b32_e32 v130, v131
	s_and_saveexec_b64 s[42:43], s[14:15]
	s_cbranch_execz .LBB0_2290
	v_ashrrev_i32_e32 v165, 31, v164
	s_waitcnt lgkmcnt(0)
	v_add_f32_e32 v132, v130, v131
	v_lshlrev_b64 v[130:131], 6, v[164:165]
	v_lshl_add_u64 v[130:131], s[88:89], 0, v[130:131]
	v_lshl_add_u64 v[130:131], s[40:41], 2, v[130:131]
	s_lshl_b32 s22, s60, 2
	v_lshl_add_u64 v[130:131], v[130:131], 0, s[22:23]
	s_and_b64 vcc, exec, s[12:13]
	s_mov_b64 s[44:45], -1
	s_cbranch_vccnz .LBB0_2288
	s_mov_b64 s[44:45], 0
	global_store_dword v[130:131], v132, off

.LBB0_2298:
	v_pk_mul_f32 v[156:157], v[192:193], v[192:193]
	v_pk_mul_f32 v[158:159], v[200:201], v[200:201]
	v_pk_mul_f32 v[192:193], v[204:205], v[204:205]
	v_pk_mul_f32 v[200:201], v[206:207], v[206:207]
	v_pk_mul_f32 v[154:155], v[190:191], v[190:191]
	v_pk_mul_f32 v[190:191], v[202:203], v[202:203]
	v_pk_mul_f32 v[160:161], v[160:161], v[160:161]
	v_pk_mul_f32 v[188:189], v[188:189], v[188:189]
	v_add_f32_e32 v163, v200, v201
	v_add_f32_e32 v169, v192, v193
	v_add_f32_e32 v163, v169, v163
	v_add_f32_e32 v169, v188, v189
	v_add_f32_e32 v160, v160, v161
	v_add_f32_e32 v161, v190, v191
	v_add_f32_e32 v158, v158, v159
	v_add_f32_e32 v156, v156, v157
	v_add_f32_e32 v154, v154, v155
	v_add_f32_e32 v160, v160, v169
	v_add_f32_e32 v158, v158, v161
	v_add_f32_e32 v154, v154, v156
	v_add_f32_e32 v160, v160, v163
	v_add_f32_e32 v154, v154, v158
	v_add_f32_e32 v154, v154, v160
	v_mov_b32_e32 v155, v154
	s_nop 1
	v_permlane16_swap_b32_e32 v154, v155
	s_mov_b64 s[44:45], s[36:37]
	s_waitcnt lgkmcnt(0)
	v_add_f32_e32 v154, v154, v155
	v_mov_b32_e32 v155, v154
	s_nop 1
	v_permlane32_swap_b32_e32 v154, v155
	s_and_saveexec_b64 s[42:43], s[14:15]
	s_cbranch_execz .LBB0_2304
	v_ashrrev_i32_e32 v185, 31, v184
	s_waitcnt lgkmcnt(0)
	v_add_f32_e32 v156, v154, v155
	v_lshlrev_b64 v[154:155], 6, v[184:185]
	v_lshl_add_u64 v[154:155], s[88:89], 0, v[154:155]
	v_lshl_add_u64 v[154:155], s[40:41], 2, v[154:155]
	s_lshl_b32 s22, s60, 2
	v_lshl_add_u64 v[154:155], v[154:155], 0, s[22:23]
	s_and_b64 vcc, exec, s[12:13]
	s_mov_b64 s[44:45], -1
	s_cbranch_vccnz .LBB0_2301
	s_mov_b64 s[44:45], 0
	global_store_dword v[154:155], v156, off

.LBB0_2312:
	v_pk_mul_f32 v[146:147], v[154:155], v[154:155]
	v_pk_mul_f32 v[148:149], v[156:157], v[156:157]
	v_pk_mul_f32 v[150:151], v[158:159], v[158:159]
	v_pk_mul_f32 v[154:155], v[160:161], v[160:161]
	v_pk_mul_f32 v[152:153], v[152:153], v[152:153]
	v_pk_mul_f32 v[156:157], v[180:181], v[180:181]
	v_pk_mul_f32 v[158:159], v[182:183], v[182:183]
	v_pk_mul_f32 v[160:161], v[184:185], v[184:185]
	v_add_f32_e32 v158, v158, v159
	v_add_f32_e32 v160, v160, v161
	v_add_f32_e32 v156, v156, v157
	v_add_f32_e32 v152, v152, v153
	v_add_f32_e32 v153, v154, v155
	v_add_f32_e32 v150, v150, v151
	v_add_f32_e32 v148, v148, v149
	v_add_f32_e32 v146, v146, v147
	v_add_f32_e32 v158, v158, v160
	v_add_f32_e32 v152, v152, v156
	v_add_f32_e32 v150, v150, v153
	v_add_f32_e32 v146, v146, v148
	v_add_f32_e32 v152, v152, v158
	v_add_f32_e32 v146, v146, v150
	v_add_f32_e32 v146, v146, v152
	v_mov_b32_e32 v147, v146
	s_nop 1
	v_permlane16_swap_b32_e32 v146, v147
	s_mov_b64 s[44:45], s[36:37]
	s_waitcnt lgkmcnt(0)
	v_add_f32_e32 v146, v146, v147
	v_mov_b32_e32 v147, v146
	s_nop 1
	v_permlane32_swap_b32_e32 v146, v147
	s_and_saveexec_b64 s[42:43], s[14:15]
	s_cbranch_execz .LBB0_2318
	v_ashrrev_i32_e32 v177, 31, v176
	s_waitcnt lgkmcnt(0)
	v_add_f32_e32 v148, v146, v147
	v_lshlrev_b64 v[146:147], 6, v[176:177]
	v_lshl_add_u64 v[146:147], s[88:89], 0, v[146:147]
	v_lshl_add_u64 v[146:147], s[40:41], 2, v[146:147]
	s_lshl_b32 s22, s60, 2
	v_lshl_add_u64 v[146:147], v[146:147], 0, s[22:23]
	s_and_b64 vcc, exec, s[12:13]
	s_mov_b64 s[44:45], -1
	s_cbranch_vccnz .LBB0_2315
	s_mov_b64 s[44:45], 0
	global_store_dword v[146:147], v148, off

.LBB0_2326:
	v_pk_mul_f32 v[138:139], v[146:147], v[146:147]
	v_pk_mul_f32 v[140:141], v[148:149], v[148:149]
	v_pk_mul_f32 v[142:143], v[150:151], v[150:151]
	v_pk_mul_f32 v[146:147], v[152:153], v[152:153]
	v_pk_mul_f32 v[144:145], v[144:145], v[144:145]
	v_pk_mul_f32 v[148:149], v[154:155], v[154:155]
	v_pk_mul_f32 v[150:151], v[156:157], v[156:157]
	v_pk_mul_f32 v[152:153], v[158:159], v[158:159]
	v_add_f32_e32 v150, v150, v151
	v_add_f32_e32 v152, v152, v153
	v_add_f32_e32 v148, v148, v149
	v_add_f32_e32 v144, v144, v145
	v_add_f32_e32 v145, v146, v147
	v_add_f32_e32 v142, v142, v143
	v_add_f32_e32 v140, v140, v141
	v_add_f32_e32 v138, v138, v139
	v_add_f32_e32 v150, v150, v152
	v_add_f32_e32 v144, v144, v148
	v_add_f32_e32 v142, v142, v145
	v_add_f32_e32 v138, v138, v140
	v_add_f32_e32 v144, v144, v150
	v_add_f32_e32 v138, v138, v142
	v_add_f32_e32 v138, v138, v144
	v_mov_b32_e32 v139, v138
	s_nop 1
	v_permlane16_swap_b32_e32 v138, v139
	s_mov_b64 s[44:45], s[36:37]
	s_waitcnt lgkmcnt(0)
	v_add_f32_e32 v138, v138, v139
	v_mov_b32_e32 v139, v138
	s_nop 1
	v_permlane32_swap_b32_e32 v138, v139
	s_and_saveexec_b64 s[42:43], s[14:15]
	s_cbranch_execz .LBB0_2332
	v_ashrrev_i32_e32 v169, 31, v168
	s_waitcnt lgkmcnt(0)
	v_add_f32_e32 v140, v138, v139
	v_lshlrev_b64 v[138:139], 6, v[168:169]
	v_lshl_add_u64 v[138:139], s[88:89], 0, v[138:139]
	v_lshl_add_u64 v[138:139], s[40:41], 2, v[138:139]
	s_lshl_b32 s22, s60, 2
	v_lshl_add_u64 v[138:139], v[138:139], 0, s[22:23]
	s_and_b64 vcc, exec, s[12:13]
	s_mov_b64 s[44:45], -1
	s_cbranch_vccnz .LBB0_2329
	s_mov_b64 s[44:45], 0
	global_store_dword v[138:139], v140, off

.LBB0_2340:
	v_pk_mul_f32 v[130:131], v[138:139], v[138:139]
	v_pk_mul_f32 v[132:133], v[140:141], v[140:141]
	v_pk_mul_f32 v[134:135], v[142:143], v[142:143]
	v_pk_mul_f32 v[138:139], v[144:145], v[144:145]
	v_pk_mul_f32 v[136:137], v[136:137], v[136:137]
	v_pk_mul_f32 v[140:141], v[146:147], v[146:147]
	v_pk_mul_f32 v[142:143], v[148:149], v[148:149]
	v_pk_mul_f32 v[144:145], v[150:151], v[150:151]
	v_add_f32_e32 v142, v142, v143
	v_add_f32_e32 v144, v144, v145
	v_add_f32_e32 v140, v140, v141
	v_add_f32_e32 v136, v136, v137
	v_add_f32_e32 v137, v138, v139
	v_add_f32_e32 v134, v134, v135
	v_add_f32_e32 v132, v132, v133
	v_add_f32_e32 v130, v130, v131
	v_add_f32_e32 v142, v142, v144
	v_add_f32_e32 v136, v136, v140
	v_add_f32_e32 v134, v134, v137
	v_add_f32_e32 v130, v130, v132
	v_add_f32_e32 v136, v136, v142
	v_add_f32_e32 v130, v130, v134
	v_add_f32_e32 v130, v130, v136
	v_mov_b32_e32 v131, v130
	s_nop 1
	v_permlane16_swap_b32_e32 v130, v131
	s_waitcnt lgkmcnt(0)
	v_add_f32_e32 v130, v130, v131
	v_mov_b32_e32 v131, v130
	s_nop 1
	v_permlane32_swap_b32_e32 v130, v131
	s_and_saveexec_b64 s[38:39], s[14:15]
	s_cbranch_execz .LBB0_2345
	v_ashrrev_i32_e32 v163, 31, v162
	s_waitcnt lgkmcnt(0)
	v_add_f32_e32 v132, v130, v131
	v_lshlrev_b64 v[130:131], 6, v[162:163]
	v_lshl_add_u64 v[130:131], s[88:89], 0, v[130:131]
	v_lshl_add_u64 v[130:131], s[40:41], 2, v[130:131]
	s_lshl_b32 s22, s60, 2
	v_lshl_add_u64 v[130:131], v[130:131], 0, s[22:23]
	s_and_b64 vcc, exec, s[12:13]
	s_mov_b64 s[12:13], -1
	s_cbranch_vccnz .LBB0_2343
	s_mov_b64 s[12:13], 0
	global_store_dword v[130:131], v132, off
